# attention A phase start: the bias table's 64 tail entries are pre-loaded by lanes 0-31 before the build loop (one pass instead of two serial ones for wave 0); on top of v88
# baseline (speedup 1.0000x reference)
; #define LAS __attribute__((address_space(3)))
; #define ATT_GLDS(g, l) __builtin_amdgcn_global_load_lds((const unsigned*)(g), (LAS unsigned*)(l), 16, 0, 0)
; __device__ __forceinline__ void lay_init(Lay& L, int lane) {
;     const int l3 = (lane >> 3) & 1, l4 = (lane >> 4) & 1, l5 = (lane >> 5) & 1, c7 = lane & 7;
;     const unsigned rows = 1024u * l3 + 512u * l5 + 256u * l4;
;     L.kOffE = rows + 16u * (unsigned)(c7 ^ (4 * l5 + 2 * l4));
;     L.kOffO = rows + 128u + 16u * (unsigned)(c7 ^ (4 * l5 + 2 * l4 + 1));
;     L.vOff = (unsigned)((lane >> 2) * 128 + (lane & 3) * 16);
;     const int r32 = lane & 31, hi = lane >> 5, kp = (r32 & ~9) | ((r32 & 1) << 3) | ((r32 >> 3) & 1), m = r32 & 7;
; #pragma unroll
;     for (int d0 = 0; d0 < 4; ++d0) L.rdK[d0] = 128 * kp + 16 * ((2 * d0 + hi) ^ m);
;     L.vrd = 4096 + ((lane >> 4) & 1) * 32 + (lane & 3) * 8 + (4 * hi + ((lane & 15) >> 2)) * 64;
; }
; __device__ __forceinline__ void dma_tile(const bf16* kt, const bf16* vt, LAS char* stage, const Lay& L) {
;     const char* kb = (const char*)kt; const char* vb = (const char*)vt + L.vOff;
;     ATT_GLDS(kb + L.kOffE, stage); ATT_GLDS(kb + L.kOffO, stage + 1024); ATT_GLDS(kb + L.kOffE + 2048, stage + 2048); ATT_GLDS(kb + L.kOffO + 2048, stage + 3072);
;     ATT_GLDS(vb, stage + 4096); ATT_GLDS(vb + 2048, stage + 5120); ATT_GLDS(vb + 64, stage + 6144); ATT_GLDS(vb + 2048 + 64, stage + 7168);
; }
; __device__ __forceinline__ void seg_start(const Seg& s, St& st, int lane) {
;     const int hi = lane >> 5;
; #pragma unroll
;     for (int d0 = 0; d0 < 4; ++d0) { st.qA[d0] = *(const bf16x8*)(s.qA + d0 * 16 + hi * 8); st.qB[d0] = *(const bf16x8*)(s.qB + d0 * 16 + hi * 8); }
; __device__ __forceinline__ void tbl_a(int u, int tblbuf, const float* t5, float cshift, LAS char* lds, int tid) {
;     const int h = (u >> 3) & 15;
;     for (int idx = tid; idx < 3 * 192; idx += NWAVES * 64) {
;         const int g = idx / 192, rel = idx % 192 - 95; const int ar = rel < 0 ? -rel : rel;
;         float v = NEG; if (ar <= 64) v = LOG2E * t5[(g * 16 + h) * 32 + t5_bucket_dev(rel << (2 * g))] - cshift;
;         ((LAS float*)(lds + TBL_OFF + tblbuf * TBL_BYTES))[idx] = v;
;     }
; }
.LBB0_302:
	s_andn2_b64 vcc, exec, s[18:19]
	s_cbranch_vccnz .LBB0_189
	v_readlane_b32 s12, v253, 20
	v_readlane_b32 s13, v253, 21
	s_waitcnt lgkmcnt(0)
	s_nop 3
	global_load_dword v153, v161, s[12:13]
	v_readlane_b32 s12, v252, 21
	v_mbcnt_lo_u32_b32 v0, -1, 0
	v_mbcnt_hi_u32_b32 v0, -1, v0
	v_readlane_b32 s13, v252, 22
	v_add_u32_e32 v158, s65, v0
	s_andn2_b64 vcc, exec, s[12:13]
	v_readfirstlane_b32 s2, v158
	s_cbranch_vccnz .LBB0_367
	v_bfe_u32 v1, v158, 4, 1
	v_bfe_u32 v3, v158, 5, 1
	v_lshlrev_b32_e32 v0, 7, v158
	v_and_b32_e32 v0, 0x400, v0
	v_lshlrev_b32_e32 v2, 9, v3
	v_lshlrev_b32_e32 v4, 8, v1
	s_ashr_i32 s2, s2, 6
	v_and_b32_e32 v6, 7, v158
	v_or3_b32 v0, v0, v2, v4
	v_lshlrev_b32_e32 v2, 2, v3
	v_lshlrev_b32_e32 v4, 1, v1
	s_lshl_b32 s12, s2, 13
	v_or_b32_e32 v5, v4, v2
	v_bitop3_b32 v2, v4, v6, v2 bitop3:0x36
	v_and_b32_e32 v7, 3, v158
	s_add_i32 s14, s12, 0
	v_lshl_or_b32 v144, v2, 4, v0
	v_bitop3_b32 v2, v5, v6, 1 bitop3:0x36
	v_lshlrev_b32_e32 v4, 5, v158
	v_lshlrev_b32_e32 v5, 4, v7
	s_movk_i32 s12, 0x780
	v_and_or_b32 v146, v4, s12, v5
	s_lshl_b32 s64, s2, 9
	v_readlane_b32 s12, v252, 23
	v_and_b32_e32 v159, 31, v158
	s_or_b32 s12, s12, s64
	v_or_b32_e32 v4, s12, v159
	v_readlane_b32 s13, v252, 25
	v_ashrrev_i32_e32 v5, 31, v4
	v_readlane_b32 s18, v252, 29
	s_add_i32 s12, s12, s13
	v_lshlrev_b64 v[4:5], 7, v[4:5]
	v_readlane_b32 s19, v252, 30
	s_ashr_i32 s13, s12, 31
	s_add_i32 s63, s14, 0x13900
	v_lshl_add_u64 v[150:151], s[18:19], 0, v[4:5]
	s_lshl_b64 s[12:13], s[12:13], 7
	v_readlane_b32 s15, v252, 26
	v_lshrrev_b32_e32 v4, 2, v158
	s_add_u32 s18, s15, s12
	v_readlane_b32 s15, v252, 27
	v_and_b32_e32 v8, 8, v4
	s_addc_u32 s19, s15, s13
	v_readlane_b32 s15, v252, 28
	v_lshlrev_b32_e32 v160, 1, v8
	v_lshl_add_u32 v148, v2, 4, v0
	v_mov_b32_e32 v149, v161
	s_add_u32 s20, s15, s12
	v_readlane_b32 s12, v252, 31
	v_lshl_add_u64 v[4:5], v[150:151], 0, v[160:161]
	v_mov_b32_e32 v145, v161
	s_mov_b32 m0, s63
	v_lshl_add_u64 v[12:13], s[18:19], 0, v[148:149]
	s_addc_u32 s21, s12, s13
	global_load_dwordx4 v[80:83], v[4:5], off
	global_load_dwordx4 v[84:87], v[4:5], off offset:32
	global_load_dwordx4 v[88:91], v[4:5], off offset:64
	global_load_dwordx4 v[92:95], v[4:5], off offset:96
	v_lshl_add_u64 v[10:11], s[18:19], 0, v[144:145]
	global_load_lds_dwordx4 v144, s[18:19]
	v_lshl_add_u64 v[14:15], v[12:13], 0, s[4:5]
	s_add_i32 m0, s14, 0x13d00
	v_lshl_add_u64 v[10:11], v[10:11], 0, s[6:7]
	global_load_lds_dwordx4 v[14:15], off
	s_add_i32 m0, s14, 0x14100
	v_mov_b32_e32 v147, v161
	global_load_lds_dwordx4 v[10:11], off
	v_lshl_add_u64 v[10:11], v[12:13], 0, s[8:9]
	s_add_i32 m0, s14, 0x14500
	v_lshl_add_u64 v[4:5], s[20:21], 0, v[146:147]
	global_load_lds_dwordx4 v[10:11], off
	s_add_i32 m0, s14, 0x14900
	v_lshl_add_u64 v[10:11], v[4:5], 0, s[6:7]
	global_load_lds_dwordx4 v146, s[20:21]
	s_add_i32 m0, s14, 0x14d00
	s_movk_i32 s12, 0x23f
	global_load_lds_dwordx4 v[10:11], off
	v_lshl_add_u64 v[10:11], v[4:5], 0, 64
	s_add_i32 m0, s14, 0x15100
	v_lshl_add_u64 v[4:5], v[4:5], 0, s[10:11]
	global_load_lds_dwordx4 v[10:11], off
	s_add_i32 m0, s14, 0x15500
	v_cmp_lt_i32_e64 s[34:35], s12, v158
	global_load_lds_dwordx4 v[4:5], off
	s_movk_i32 s12, 0x240
	v_cmp_gt_i32_e32 vcc, s12, v158
	v_sub_u32_e32 v166, 0x5f, v158
	s_and_saveexec_b64 s[22:23], vcc
	s_cbranch_execz .LBB0_311
	v_sub_u32_e32 v0, 0x5f, v158
	v_lshl_add_u32 v9, v158, 2, s1
	s_mov_b64 s[24:25], 0
	v_mov_b32_e32 v2, v158
	v_cmp_gt_u32_e32 vcc, 32, v158
	s_and_saveexec_b64 s[26:27], vcc
	v_cmp_lt_u32_e32 vcc, 1, v158
	s_nop 1
	v_cndmask_b32_e64 v230, 14, 15, vcc
	v_add_u32_e32 v230, 0x410, v230
	v_add_u32_e32 v230, s92, v230
	v_lshlrev_b32_e32 v230, 2, v230
	global_load_dword v231, v230, s[56:57]
	s_or_b64 exec, exec, s[26:27]
	s_branch .LBB0_308

; #define LAS __attribute__((address_space(3)))
; __device__ __forceinline__ void tbl_a(int u, int tblbuf, const float* t5, float cshift, LAS char* lds, int tid) {
;     ...
;     for (int idx = tid; idx < 3 * 192; idx += NWAVES * 64) {
;         const int g = idx / 192, rel = idx % 192 - 95; const int ar = rel < 0 ? -rel : rel;
;         float v = NEG; if (ar <= 64) v = LOG2E * t5[(g * 16 + h) * 32 + t5_bucket_dev(rel << (2 * g))] - cshift;
;         ((LAS float*)(lds + TBL_OFF + tblbuf * TBL_BYTES))[idx] = v;
;     }
.LBB0_307:
	s_or_b64 exec, exec, s[26:27]
	v_add_u32_e32 v4, 0x200, v2
	v_cmp_lt_i32_e32 vcc, -1, v2
	ds_write_b32 v9, v11
	v_add_u32_e32 v0, 0xfffffe00, v0
	v_add_u32_e32 v9, 0x800, v9
	s_or_b64 s[24:25], vcc, s[24:25]
	v_mov_b32_e32 v2, v4
	s_andn2_b64 exec, exec, s[24:25]
	s_cbranch_execz .LBB0_311

; #define LAS __attribute__((address_space(3)))
; __device__ __forceinline__ void tbl_a(int u, int tblbuf, const float* t5, float cshift, LAS char* lds, int tid) {
;     ...
;         float v = NEG; if (ar <= 64) v = LOG2E * t5[(g * 16 + h) * 32 + t5_bucket_dev(rel << (2 * g))] - cshift;
;         ((LAS float*)(lds + TBL_OFF + tblbuf * TBL_BYTES))[idx] = v;
; __device__ __forceinline__ void attn_a_phase(Frame& F, const float cshift, const bf16* qkv, const bf16* gate, bf16* y, const float* t5, const float* qg, const float* kg) {
;     ...
;     Lay L; lay_init(L, lane);
;     Seg cur; St st;
;     seg_a(cur, u0, 0, 0, qkv, lds, lane, wave); seg_start(cur, st, lane); dma_tile(cur.kt, cur.vt, stage, L);
;     tbl_a(u0, 0, t5, cshift, lds, tid);
;     __syncthreads();
; #pragma unroll 1
;     for (int ui = 0; ui < nu; ++ui) {
.LBB0_311:
	s_or_b64 exec, exec, s[22:23]
	v_cmp_gt_u32_e32 vcc, 64, v158
	s_and_saveexec_b64 s[26:27], vcc
	s_cbranch_execz .Ltb2_skip
	s_waitcnt vmcnt(0)
	v_mov_b32_e32 v232, 0xf149f2ca
	v_fma_f32 v233, v231, s71, -v153
	v_cmp_gt_u32_e32 vcc, 32, v158
	s_nop 1
	v_cndmask_b32_e32 v232, v232, v233, vcc
	v_lshl_add_u32 v234, v158, 2, s1
	v_add_u32_e32 v234, 0x800, v234
	ds_write_b32 v234, v232
.Ltb2_skip:
	s_or_b64 exec, exec, s[26:27]
	v_and_b32_e32 v0, 63, v158
	v_lshrrev_b32_e32 v5, 3, v0
	v_and_b32_e32 v5, 4, v5
	v_lshlrev_b32_e32 v4, 3, v0
	v_sub_u32_e32 v12, v5, v159
	v_and_b32_e32 v2, 22, v158
	v_and_b32_e32 v4, 8, v4
	v_bfe_u32 v9, v0, 3, 1
	s_lshl_b32 s65, s2, 1
	v_add_u32_e32 v167, 0x19f, v12
	v_readlane_b32 s2, v252, 24
	v_or3_b32 v2, v4, v2, v9
	v_xor_b32_e32 v4, v3, v6
	v_bitop3_b32 v9, v3, v6, 2 bitop3:0x36
	v_bitop3_b32 v10, v3, v6, 4 bitop3:0x36
	v_bitop3_b32 v6, v3, v6, 6 bitop3:0x36
	v_lshlrev_b32_e32 v7, 3, v7
	v_lshlrev_b32_e32 v3, 8, v3
	v_lshlrev_b32_e32 v11, 4, v0
	v_add_u32_e32 v12, s2, v167
	v_lshl_add_u32 v168, v159, 4, s65
	v_lshl_add_u32 v1, v1, 5, s63
	v_lshlrev_b32_e32 v2, 7, v2
	v_and_b32_e32 v11, 0xc0, v11
	v_lshl_add_u32 v179, v12, 2, s1
	v_add_u32_e32 v169, 0x200, v168
	v_add_u32_e32 v152, 0, v8
	v_xad_u32 v171, v159, 31, v5
	v_lshl_add_u32 v4, v4, 4, s63
	v_lshl_add_u32 v5, v9, 4, s63
	v_lshl_add_u32 v8, v10, 4, s63
	v_lshl_add_u32 v6, v6, 4, s63
	v_add3_u32 v1, v1, v7, v3
	s_waitcnt vmcnt(0)
	v_mov_b64_e32 v[98:99], v[82:83]
	v_mov_b64_e32 v[102:103], v[86:87]
	v_mov_b64_e32 v[106:107], v[90:91]
	v_mov_b64_e32 v[110:111], v[94:95]
	s_mov_b32 s60, 1
	v_add_u32_e32 v180, 0xffffff80, v179
	v_or_b32_e32 v170, 32, v159
	v_cmp_gt_u32_e64 s[36:37], 32, v0
	s_mov_b32 s67, 0
	s_movk_i32 s66, 0x1000
	v_mov_b32_e32 v178, 0
	v_mov_b32_e32 v177, 1
	v_add_u32_e32 v172, v4, v2
	v_add_u32_e32 v173, v5, v2
	v_add_u32_e32 v174, v8, v2
	v_add_u32_e32 v175, v6, v2
	v_add_u32_e32 v176, v1, v11
	s_add_i32 s78, s63, 0xc00
	s_add_i32 s79, s63, 0x1400
	s_add_i32 s80, s63, 0x1800
	s_add_i32 s81, s63, 0x1c00
	v_mov_b64_e32 v[96:97], v[80:81]
	v_mov_b64_e32 v[100:101], v[84:85]
	v_mov_b64_e32 v[104:105], v[88:89]
	v_mov_b64_e32 v[108:109], v[92:93]
	v_mov_b64_e32 v[154:155], v[150:151]
	v_readlane_b32 s87, v252, 32
	v_readlane_b32 s14, v252, 33
	s_mov_b32 s82, 0
	v_mov_b32_e32 v181, v168
	v_mov_b32_e32 v182, v169
	s_waitcnt lgkmcnt(0)
	s_barrier
	s_branch .LBB0_313
